# also w_o and w_gdn_up conversions moved from phase 0 into the phase-3 shadow
# speedup vs baseline: 1.0306x; 1.0033x over previous
; #define LAS __attribute__((address_space(3)))
; __device__ __forceinline__ void convert_items(const Params& p, LAS float* scr, int lane, int gw, int NGW, int it_lo, int it_hi) {
;     unsigned char* ws = p.ws;
;     for (int it = it_lo + gw; it < it_hi; it += NGW) {
;         int r = it;
;         if (r < CV_WIN) { const int kb = r / 417, nb = r % 417, ns = nb * 32; const int nd = ns < 9216 ? ns : (ns < 9248 ? 13312 + (ns - 9216) : ns - 32);
;             transpose_item(p.in[8], IN_COLS, 2048, (bf16_t*)(ws + WS_WIN), kb * 64, ns, nd, scr, lane); continue; } r -= CV_WIN;
; __device__ __forceinline__ void phase0(const Params& p, LAS unsigned char* lds, int wave_s) {
;     const int tid = opaque_tid(wave_s), lane = tid & 63, wave = tid >> 6;
;     const int gw = blockIdx.x * 8 + wave, NGW = gridDim.x * 8;
;     LAS float* scr = (LAS float*)(lds + wave * 8448);
;     unsigned char* ws = p.ws;
;     convert_items(p, scr, lane, gw, NGW, 0, CV_SPLIT);
.LBB0_17:
	s_or_b64 exec, exec, s[0:1]
	s_andn2_b32 s24, s24, 63
	s_cmp_lt_i32 s18, 1
	s_cselect_b64 s[0:1], -1, 0
	s_cmp_gt_i32 s19, 0
	s_cselect_b64 s[4:5], -1, 0
	s_and_b64 s[0:1], s[0:1], s[4:5]
	s_andn2_b64 vcc, exec, s[0:1]
	s_waitcnt lgkmcnt(0)
	s_barrier
	s_cbranch_vccnz .LBB0_70
	s_mov_b32 s3, 0
	s_lshl_b32 s4, s33, 3
	v_mbcnt_lo_u32_b32 v0, -1, s3
	v_mbcnt_hi_u32_b32 v0, -1, v0
	v_or_b32_e32 v13, s24, v0
	s_movk_i32 s3, 0x38a0
	v_ashrrev_i32_e32 v28, 6, v13
	v_and_b32_e32 v16, 63, v13
	v_lshl_add_u32 v12, s2, 3, v28
	v_cmp_gt_i32_e32 vcc, s3, v12
	v_lshlrev_b32_e32 v14, 3, v16
	s_and_saveexec_b64 s[6:7], vcc
	s_cbranch_execz .LBB0_45
	s_movk_i32 s3, 0x2100
	v_mul_lo_u32 v0, v28, s3
	v_lshrrev_b32_e32 v15, 5, v16
	v_and_b32_e32 v30, 31, v13
	v_add_u32_e32 v0, 0, v0
	v_lshlrev_b32_e32 v26, 2, v30
	v_mul_u32_u24_e32 v2, 0x84, v15
	v_lshrrev_b32_e32 v34, 3, v16
	v_and_b32_e32 v32, 56, v14
	v_add3_u32 v17, v0, v26, v2
	v_mul_u32_u24_e32 v2, 0x84, v32
	v_lshlrev_b32_e32 v3, 2, v34
	v_mov_b32_e32 v1, 0
	v_add3_u32 v35, v0, v2, v3
	v_lshlrev_b32_e32 v0, 1, v32
	v_lshl_add_u64 v[10:11], s[22:23], 0, v[0:1]
	s_mov_b64 s[8:9], 0x1480000
	v_lshl_add_u64 v[2:3], v[10:11], 0, s[8:9]
	s_mov_b64 s[8:9], 0xc80000
	v_lshl_add_u64 v[4:5], v[10:11], 0, s[8:9]
	s_mov_b64 s[8:9], 0x480000
	v_lshlrev_b32_e32 v0, 5, v28
	v_lshl_add_u64 v[6:7], v[10:11], 0, s[8:9]
	s_mov_b64 s[8:9], 0x80000
	v_readlane_b32 s36, v254, 0
	v_lshl_add_u32 v39, s2, 8, v0
	v_lshlrev_b32_e32 v0, 11, v28
	v_lshl_add_u64 v[8:9], v[10:11], 0, s[8:9]
	s_mov_b64 s[8:9], 0x64aa000
	v_mov_b32_e32 v27, v1
	v_readlane_b32 s37, v254, 1
	v_readlane_b32 s38, v254, 2
	v_readlane_b32 s39, v254, 3
	v_readlane_b32 s40, v254, 4
	v_readlane_b32 s41, v254, 5
	v_readlane_b32 s42, v254, 6
	v_readlane_b32 s43, v254, 7
	v_readlane_b32 s44, v254, 8
	v_readlane_b32 s45, v254, 9
	v_readlane_b32 s46, v254, 10
	v_readlane_b32 s47, v254, 11
	v_readlane_b32 s48, v254, 12
	v_lshl_add_u32 v40, s2, 14, v0
	v_lshlrev_b32_e32 v0, 3, v28
	v_or_b32_e32 v36, 8, v34
	v_or_b32_e32 v37, 16, v34
	v_or_b32_e32 v38, 24, v34
	v_lshl_add_u64 v[10:11], v[10:11], 0, s[8:9]
	v_lshl_add_u64 v[18:19], s[42:43], 0, v[26:27]
	v_lshl_add_u64 v[20:21], s[38:39], 0, v[26:27]
	v_lshl_add_u64 v[22:23], s[36:37], 0, v[26:27]
	v_lshl_add_u64 v[24:25], s[82:83], 0, v[26:27]
	v_lshl_add_u64 v[26:27], s[68:69], 0, v[26:27]
	s_lshl_b32 s3, s4, 5
	s_lshl_b32 s5, s4, 11
	v_lshl_add_u32 v41, s2, 6, v0
	s_lshl_b32 s25, s4, 3
	s_mov_b64 s[8:9], 0
	v_lshlrev_b32_e32 v28, 2, v30
	s_movk_i32 s30, 0x3000
	s_movk_i32 s31, 0x4000
	s_movk_i32 s34, 0x5000
	s_movk_i32 s35, 0x6000
	s_movk_i32 s36, 0x7000
	s_mov_b32 s37, 0x8000
	s_mov_b32 s38, 0x9000
	s_mov_b32 s39, 0xa000
	s_mov_b32 s40, 0xb000
	s_mov_b32 s41, 0xc000
	s_mov_b32 s42, 0xd000
	s_mov_b32 s43, 0xe000
	s_mov_b32 s44, 0xf000
	v_lshlrev_b32_e32 v30, 1, v32
	s_mov_b32 s45, 0x274a4871
	s_movk_i32 s46, 0x120
	s_mov_b32 s47, 0xd080
	s_movk_i32 s48, 0x389f
	v_mov_b32_e32 v42, 6
	v_add_u32_e32 v43, 0x400, v17
	v_add_u32_e32 v44, 0x800, v17
	v_mov_b32_e32 v45, 0x3400
	v_mov_b32_e32 v46, v12
	v_readlane_b32 s49, v254, 13
	v_readlane_b32 s50, v254, 14
	v_readlane_b32 s51, v254, 15
	s_branch .LBB0_21

; #define LAS __attribute__((address_space(3)))
; __device__ __forceinline__ unsigned pk2(float lo, float hi) { const f32x2_t v = {lo, hi}; const bf16x2_t b = __builtin_convertvector(v, bf16x2_t); return __builtin_bit_cast(unsigned, b); }
; #define LDS_WAIT() asm volatile("s_waitcnt lgkmcnt(0)" ::: "memory")
; __device__ __forceinline__ void transpose_item(const float* W, int N, int K, bf16_t* WT, int k0, int n0src, int n0dst, LAS float* scr, int lane) {
;     float tv[32];
; #pragma unroll
;     for (int i = 0; i < 32; ++i) tv[i] = __builtin_nontemporal_load(&W[(size_t)(k0 + 2 * i + (lane >> 5)) * N + n0src + (lane & 31)]);
; #pragma unroll
;     for (int i = 0; i < 32; ++i) scr[(2 * i + (lane >> 5)) * 33 + (lane & 31)] = tv[i];
;     LDS_WAIT();
;     const int c = lane & 7;
; #pragma unroll
;     for (int j = 0; j < 4; ++j) { const int n = (lane >> 3) + 8 * j; const LAS float* s = scr + (8 * c) * 33 + n;
;         u32x4 o; o.x = pk2(s[0 * 33], s[1 * 33]); o.y = pk2(s[2 * 33], s[3 * 33]); o.z = pk2(s[4 * 33], s[5 * 33]); o.w = pk2(s[6 * 33], s[7 * 33]);
;         *(u32x4*)(WT + (size_t)(n0dst + n) * K + k0 + 8 * c) = o; }
;     LDS_WAIT();
; }
; __device__ __forceinline__ void convert_items(const Params& p, LAS float* scr, int lane, int gw, int NGW, int it_lo, int it_hi) {
;     ...
;         if (r < CV_GATE) { const int kb = r / 352, nb = r % 352, ns = nb * 32; int nd; if (ns < DFF) nd = 256 * (ns / 128) + (ns % 128); else { const int j = ns - DFF; nd = 256 * (j / 128) + 128 + (j % 128); }
;             transpose_item(p.in[19], 2 * DFF, 2048, (bf16_t*)(ws + WS_WGATE), kb * 64, ns, nd, scr, lane); continue; } r -= CV_GATE;
.LBB0_896:
	s_or_b64 exec, exec, s[0:1]
	s_mov_b64 exec, -1
	v_mbcnt_lo_u32_b32 v0, -1, 0
	v_mbcnt_hi_u32_b32 v0, -1, v0
	s_lshr_b32 s84, s24, 6
	s_sub_i32 s85, s2, 64
	s_lshl_b32 s85, s85, 3
	s_add_i32 s85, s85, s84
	v_readlane_b32 s86, v254, 6
	v_readlane_b32 s87, v254, 7
	s_mul_i32 s90, s84, 0x2100
	v_lshrrev_b32_e32 v1, 5, v0
	v_and_b32_e32 v2, 31, v0
	v_mul_u32_u24_e32 v3, 0xb000, v1
	v_lshl_add_u32 v3, v2, 2, v3
	v_mul_u32_u24_e32 v4, 33, v1
	v_add_u32_e32 v4, v4, v2
	v_lshl_add_u32 v4, v4, 2, s90
	v_and_b32_e32 v5, 7, v0
	v_lshrrev_b32_e32 v6, 3, v0
	v_mul_u32_u24_e32 v7, 0x420, v5
	v_lshl_add_u32 v7, v6, 2, v7
	v_add_u32_e32 v7, s90, v7
	v_mul_u32_u24_e32 v8, 0x1000, v6
	v_lshl_add_u32 v8, v5, 4, v8
	v_add_u32_e32 v9, 0x8000, v8
	v_add_u32_e32 v10, 0x10000, v8
	v_add_u32_e32 v11, 0x18000, v8
.Lgconv_gate_loop:
	s_cmp_lt_u32 s85, 0x2c00
	s_cbranch_scc0 .Lgconv_gate_done
	s_mul_i32 s91, s85, 0xba2f
	s_lshr_b32 s91, s91, 24
	s_mul_i32 s92, s91, 0x160
	s_sub_i32 s92, s85, s92
	s_lshl_b32 s92, s92, 5
	s_cmp_lt_u32 s92, 0x1600
	s_cselect_b32 s93, 0, 0x1600
	s_cselect_b32 s94, 0, 0x80
	s_sub_i32 s93, s92, s93
	s_lshr_b32 s95, s93, 7
	s_lshl_b32 s95, s95, 8
	s_and_b32 s93, s93, 0x7f
	s_add_i32 s95, s95, s93
	s_add_i32 s95, s95, s94
	s_mul_i32 s96, s91, 0x2c0000
	s_lshl_b32 s97, s92, 2
	s_add_i32 s96, s96, s97
	s_add_u32 s96, s86, s96
	s_addc_u32 s97, s87, 0
	global_load_dword v16, v3, s[96:97] nt
	s_add_u32 s96, s96, 0x16000
	s_addc_u32 s97, s97, 0
	global_load_dword v17, v3, s[96:97] nt
	s_add_u32 s96, s96, 0x16000
	s_addc_u32 s97, s97, 0
	global_load_dword v18, v3, s[96:97] nt
	s_add_u32 s96, s96, 0x16000
	s_addc_u32 s97, s97, 0
	global_load_dword v19, v3, s[96:97] nt
	s_add_u32 s96, s96, 0x16000
	s_addc_u32 s97, s97, 0
	global_load_dword v20, v3, s[96:97] nt
	s_add_u32 s96, s96, 0x16000
	s_addc_u32 s97, s97, 0
	global_load_dword v21, v3, s[96:97] nt
	s_add_u32 s96, s96, 0x16000
	s_addc_u32 s97, s97, 0
	global_load_dword v22, v3, s[96:97] nt
	s_add_u32 s96, s96, 0x16000
	s_addc_u32 s97, s97, 0
	global_load_dword v23, v3, s[96:97] nt
	s_add_u32 s96, s96, 0x16000
	s_addc_u32 s97, s97, 0
	global_load_dword v24, v3, s[96:97] nt
	s_add_u32 s96, s96, 0x16000
	s_addc_u32 s97, s97, 0
	global_load_dword v25, v3, s[96:97] nt
	s_add_u32 s96, s96, 0x16000
	s_addc_u32 s97, s97, 0
	global_load_dword v26, v3, s[96:97] nt
	s_add_u32 s96, s96, 0x16000
	s_addc_u32 s97, s97, 0
	global_load_dword v27, v3, s[96:97] nt
	s_add_u32 s96, s96, 0x16000
	s_addc_u32 s97, s97, 0
	global_load_dword v28, v3, s[96:97] nt
	s_add_u32 s96, s96, 0x16000
	s_addc_u32 s97, s97, 0
	global_load_dword v29, v3, s[96:97] nt
	s_add_u32 s96, s96, 0x16000
	s_addc_u32 s97, s97, 0
	global_load_dword v30, v3, s[96:97] nt
	s_add_u32 s96, s96, 0x16000
	s_addc_u32 s97, s97, 0
	global_load_dword v31, v3, s[96:97] nt
	s_add_u32 s96, s96, 0x16000
	s_addc_u32 s97, s97, 0
	global_load_dword v32, v3, s[96:97] nt
	s_add_u32 s96, s96, 0x16000
	s_addc_u32 s97, s97, 0
	global_load_dword v33, v3, s[96:97] nt
	s_add_u32 s96, s96, 0x16000
	s_addc_u32 s97, s97, 0
	global_load_dword v34, v3, s[96:97] nt
	s_add_u32 s96, s96, 0x16000
	s_addc_u32 s97, s97, 0
	global_load_dword v35, v3, s[96:97] nt
	s_add_u32 s96, s96, 0x16000
	s_addc_u32 s97, s97, 0
	global_load_dword v36, v3, s[96:97] nt
	s_add_u32 s96, s96, 0x16000
	s_addc_u32 s97, s97, 0
	global_load_dword v37, v3, s[96:97] nt
	s_add_u32 s96, s96, 0x16000
	s_addc_u32 s97, s97, 0
	global_load_dword v38, v3, s[96:97] nt
	s_add_u32 s96, s96, 0x16000
	s_addc_u32 s97, s97, 0
	global_load_dword v39, v3, s[96:97] nt
	s_add_u32 s96, s96, 0x16000
	s_addc_u32 s97, s97, 0
	global_load_dword v40, v3, s[96:97] nt
	s_add_u32 s96, s96, 0x16000
	s_addc_u32 s97, s97, 0
	global_load_dword v41, v3, s[96:97] nt
	s_add_u32 s96, s96, 0x16000
	s_addc_u32 s97, s97, 0
	global_load_dword v42, v3, s[96:97] nt
	s_add_u32 s96, s96, 0x16000
	s_addc_u32 s97, s97, 0
	global_load_dword v43, v3, s[96:97] nt
	s_add_u32 s96, s96, 0x16000
	s_addc_u32 s97, s97, 0
	global_load_dword v44, v3, s[96:97] nt
	s_add_u32 s96, s96, 0x16000
	s_addc_u32 s97, s97, 0
	global_load_dword v45, v3, s[96:97] nt
	s_add_u32 s96, s96, 0x16000
	s_addc_u32 s97, s97, 0
	global_load_dword v46, v3, s[96:97] nt
	s_add_u32 s96, s96, 0x16000
	s_addc_u32 s97, s97, 0
	global_load_dword v47, v3, s[96:97] nt
	s_mul_i32 s92, s95, 0x1000
	s_lshl_b32 s93, s91, 7
	s_add_i32 s92, s92, s93
	s_add_u32 s92, s22, s92
	s_addc_u32 s93, s23, 0
	s_add_u32 s92, s92, 0x1480000
	s_addc_u32 s93, s93, 0
	s_waitcnt vmcnt(31)
	ds_write_b32 v4, v16
	s_waitcnt vmcnt(30)
	ds_write_b32 v4, v17 offset:264
	s_waitcnt vmcnt(29)
	ds_write_b32 v4, v18 offset:528
	s_waitcnt vmcnt(28)
	ds_write_b32 v4, v19 offset:792
	s_waitcnt vmcnt(27)
	ds_write_b32 v4, v20 offset:1056
	s_waitcnt vmcnt(26)
	ds_write_b32 v4, v21 offset:1320
	s_waitcnt vmcnt(25)
	ds_write_b32 v4, v22 offset:1584
	s_waitcnt vmcnt(24)
	ds_write_b32 v4, v23 offset:1848
	s_waitcnt vmcnt(23)
	ds_write_b32 v4, v24 offset:2112
	s_waitcnt vmcnt(22)
	ds_write_b32 v4, v25 offset:2376
	s_waitcnt vmcnt(21)
	ds_write_b32 v4, v26 offset:2640
	s_waitcnt vmcnt(20)
	ds_write_b32 v4, v27 offset:2904
	s_waitcnt vmcnt(19)
	ds_write_b32 v4, v28 offset:3168
	s_waitcnt vmcnt(18)
	ds_write_b32 v4, v29 offset:3432
	s_waitcnt vmcnt(17)
	ds_write_b32 v4, v30 offset:3696
	s_waitcnt vmcnt(16)
	ds_write_b32 v4, v31 offset:3960
	s_waitcnt vmcnt(15)
	ds_write_b32 v4, v32 offset:4224
	s_waitcnt vmcnt(14)
	ds_write_b32 v4, v33 offset:4488
	s_waitcnt vmcnt(13)
	ds_write_b32 v4, v34 offset:4752
	s_waitcnt vmcnt(12)
	ds_write_b32 v4, v35 offset:5016
	s_waitcnt vmcnt(11)
	ds_write_b32 v4, v36 offset:5280
	s_waitcnt vmcnt(10)
; #define LAS __attribute__((address_space(3)))
; __device__ __forceinline__ unsigned pk2(float lo, float hi) { const f32x2_t v = {lo, hi}; const bf16x2_t b = __builtin_convertvector(v, bf16x2_t); return __builtin_bit_cast(unsigned, b); }
; #define LDS_WAIT() asm volatile("s_waitcnt lgkmcnt(0)" ::: "memory")
; __device__ __forceinline__ void transpose_item(const float* W, int N, int K, bf16_t* WT, int k0, int n0src, int n0dst, LAS float* scr, int lane) {
;     ...
;     for (int i = 0; i < 32; ++i) scr[(2 * i + (lane >> 5)) * 33 + (lane & 31)] = tv[i];
;     LDS_WAIT();
;     const int c = lane & 7;
; #pragma unroll
;     for (int j = 0; j < 4; ++j) { const int n = (lane >> 3) + 8 * j; const LAS float* s = scr + (8 * c) * 33 + n;
;         u32x4 o; o.x = pk2(s[0 * 33], s[1 * 33]); o.y = pk2(s[2 * 33], s[3 * 33]); o.z = pk2(s[4 * 33], s[5 * 33]); o.w = pk2(s[6 * 33], s[7 * 33]);
;         *(u32x4*)(WT + (size_t)(n0dst + n) * K + k0 + 8 * c) = o; }
;     LDS_WAIT();
; }
; __device__ __forceinline__ void convert_items(const Params& p, LAS float* scr, int lane, int gw, int NGW, int it_lo, int it_hi) {
;     ...
;         if (r < CV_2K) { const int kb = r / 64, nb = r % 64; transpose_item(p.in[17], 2048, 2048, (bf16_t*)(ws + WS_WO), kb * 64, nb * 32, nb * 32, scr, lane); continue; } r -= CV_2K;
	ds_write_b32 v4, v37 offset:5544
	s_waitcnt vmcnt(9)
	ds_write_b32 v4, v38 offset:5808
	s_waitcnt vmcnt(8)
	ds_write_b32 v4, v39 offset:6072
	s_waitcnt vmcnt(7)
	ds_write_b32 v4, v40 offset:6336
	s_waitcnt vmcnt(6)
	ds_write_b32 v4, v41 offset:6600
	s_waitcnt vmcnt(5)
	ds_write_b32 v4, v42 offset:6864
	s_waitcnt vmcnt(4)
	ds_write_b32 v4, v43 offset:7128
	s_waitcnt vmcnt(3)
	ds_write_b32 v4, v44 offset:7392
	s_waitcnt vmcnt(2)
	ds_write_b32 v4, v45 offset:7656
	s_waitcnt vmcnt(1)
	ds_write_b32 v4, v46 offset:7920
	s_waitcnt vmcnt(0)
	ds_write_b32 v4, v47 offset:8184
	s_waitcnt lgkmcnt(0)
	ds_read_b32 v48, v7
	ds_read_b32 v49, v7 offset:132
	ds_read_b32 v50, v7 offset:264
	ds_read_b32 v51, v7 offset:396
	ds_read_b32 v52, v7 offset:528
	ds_read_b32 v53, v7 offset:660
	ds_read_b32 v54, v7 offset:792
	ds_read_b32 v55, v7 offset:924
	s_waitcnt lgkmcnt(0)
	v_cvt_pk_bf16_f32 v80, v48, v49
	v_cvt_pk_bf16_f32 v81, v50, v51
	v_cvt_pk_bf16_f32 v82, v52, v53
	v_cvt_pk_bf16_f32 v83, v54, v55
	global_store_dwordx4 v8, v[80:83], s[92:93]
	ds_read_b32 v56, v7 offset:32
	ds_read_b32 v57, v7 offset:164
	ds_read_b32 v58, v7 offset:296
	ds_read_b32 v59, v7 offset:428
	ds_read_b32 v60, v7 offset:560
	ds_read_b32 v61, v7 offset:692
	ds_read_b32 v62, v7 offset:824
	ds_read_b32 v63, v7 offset:956
	s_waitcnt lgkmcnt(0)
	v_cvt_pk_bf16_f32 v84, v56, v57
	v_cvt_pk_bf16_f32 v85, v58, v59
	v_cvt_pk_bf16_f32 v86, v60, v61
	v_cvt_pk_bf16_f32 v87, v62, v63
	global_store_dwordx4 v9, v[84:87], s[92:93]
	ds_read_b32 v64, v7 offset:64
	ds_read_b32 v65, v7 offset:196
	ds_read_b32 v66, v7 offset:328
	ds_read_b32 v67, v7 offset:460
	ds_read_b32 v68, v7 offset:592
	ds_read_b32 v69, v7 offset:724
	ds_read_b32 v70, v7 offset:856
	ds_read_b32 v71, v7 offset:988
	s_waitcnt lgkmcnt(0)
	v_cvt_pk_bf16_f32 v88, v64, v65
	v_cvt_pk_bf16_f32 v89, v66, v67
	v_cvt_pk_bf16_f32 v90, v68, v69
	v_cvt_pk_bf16_f32 v91, v70, v71
	global_store_dwordx4 v10, v[88:91], s[92:93]
	ds_read_b32 v72, v7 offset:96
	ds_read_b32 v73, v7 offset:228
	ds_read_b32 v74, v7 offset:360
	ds_read_b32 v75, v7 offset:492
	ds_read_b32 v76, v7 offset:624
	ds_read_b32 v77, v7 offset:756
	ds_read_b32 v78, v7 offset:888
	ds_read_b32 v79, v7 offset:1020
	s_waitcnt lgkmcnt(0)
	v_cvt_pk_bf16_f32 v92, v72, v73
	v_cvt_pk_bf16_f32 v93, v74, v75
	v_cvt_pk_bf16_f32 v94, v76, v77
	v_cvt_pk_bf16_f32 v95, v78, v79
	global_store_dwordx4 v11, v[92:95], s[92:93]
	s_add_i32 s85, s85, 0x600
	s_branch .Lgconv_gate_loop
.Lgconv_gate_done:
	s_mov_b64 exec, -1
	v_mbcnt_lo_u32_b32 v0, -1, 0
	v_mbcnt_hi_u32_b32 v0, -1, v0
	s_lshr_b32 s84, s24, 6
	s_sub_i32 s85, s2, 64
	s_lshl_b32 s85, s85, 3
	s_add_i32 s85, s85, s84
	v_readlane_b32 s86, v254, 2
	v_readlane_b32 s87, v254, 3
	s_mul_i32 s90, s84, 0x2100
	v_lshrrev_b32_e32 v1, 5, v0
	v_and_b32_e32 v2, 31, v0
	v_mul_u32_u24_e32 v3, 0x2000, v1
	v_lshl_add_u32 v3, v2, 2, v3
	v_mul_u32_u24_e32 v4, 33, v1
	v_add_u32_e32 v4, v4, v2
	v_lshl_add_u32 v4, v4, 2, s90
	v_and_b32_e32 v5, 7, v0
	v_lshrrev_b32_e32 v6, 3, v0
	v_mul_u32_u24_e32 v7, 0x420, v5
	v_lshl_add_u32 v7, v6, 2, v7
	v_add_u32_e32 v7, s90, v7
	v_mul_u32_u24_e32 v8, 0x1000, v6
	v_lshl_add_u32 v8, v5, 4, v8
	v_add_u32_e32 v9, 0x8000, v8
	v_add_u32_e32 v10, 0x10000, v8
	v_add_u32_e32 v11, 0x18000, v8
.Lgconv_wo_loop:
	s_cmp_lt_u32 s85, 0x800
	s_cbranch_scc0 .Lgconv_wo_done
	s_lshr_b32 s91, s85, 6
	s_mul_i32 s92, s91, 0x40
	s_sub_i32 s92, s85, s92
	s_lshl_b32 s92, s92, 5
	s_mov_b32 s95, s92
	s_mul_i32 s96, s91, 0x80000
	s_lshl_b32 s97, s92, 2
	s_add_i32 s96, s96, s97
	s_add_u32 s96, s86, s96
	s_addc_u32 s97, s87, 0
	global_load_dword v16, v3, s[96:97] nt
	s_add_u32 s96, s96, 0x4000
	s_addc_u32 s97, s97, 0
	global_load_dword v17, v3, s[96:97] nt
	s_add_u32 s96, s96, 0x4000
	s_addc_u32 s97, s97, 0
	global_load_dword v18, v3, s[96:97] nt
	s_add_u32 s96, s96, 0x4000
	s_addc_u32 s97, s97, 0
	global_load_dword v19, v3, s[96:97] nt
	s_add_u32 s96, s96, 0x4000
	s_addc_u32 s97, s97, 0
	global_load_dword v20, v3, s[96:97] nt
	s_add_u32 s96, s96, 0x4000
	s_addc_u32 s97, s97, 0
	global_load_dword v21, v3, s[96:97] nt
	s_add_u32 s96, s96, 0x4000
	s_addc_u32 s97, s97, 0
	global_load_dword v22, v3, s[96:97] nt
	s_add_u32 s96, s96, 0x4000
	s_addc_u32 s97, s97, 0
	global_load_dword v23, v3, s[96:97] nt
	s_add_u32 s96, s96, 0x4000
	s_addc_u32 s97, s97, 0
	global_load_dword v24, v3, s[96:97] nt
	s_add_u32 s96, s96, 0x4000
	s_addc_u32 s97, s97, 0
	global_load_dword v25, v3, s[96:97] nt
	s_add_u32 s96, s96, 0x4000
	s_addc_u32 s97, s97, 0
	global_load_dword v26, v3, s[96:97] nt
	s_add_u32 s96, s96, 0x4000
	s_addc_u32 s97, s97, 0
	global_load_dword v27, v3, s[96:97] nt
	s_add_u32 s96, s96, 0x4000
	s_addc_u32 s97, s97, 0
	global_load_dword v28, v3, s[96:97] nt
	s_add_u32 s96, s96, 0x4000
	s_addc_u32 s97, s97, 0
	global_load_dword v29, v3, s[96:97] nt
	s_add_u32 s96, s96, 0x4000
	s_addc_u32 s97, s97, 0
	global_load_dword v30, v3, s[96:97] nt
	s_add_u32 s96, s96, 0x4000
	s_addc_u32 s97, s97, 0
	global_load_dword v31, v3, s[96:97] nt
	s_add_u32 s96, s96, 0x4000
	s_addc_u32 s97, s97, 0
	global_load_dword v32, v3, s[96:97] nt
	s_add_u32 s96, s96, 0x4000
	s_addc_u32 s97, s97, 0
	global_load_dword v33, v3, s[96:97] nt
	s_add_u32 s96, s96, 0x4000
	s_addc_u32 s97, s97, 0
	global_load_dword v34, v3, s[96:97] nt
	s_add_u32 s96, s96, 0x4000
	s_addc_u32 s97, s97, 0
	global_load_dword v35, v3, s[96:97] nt
	s_add_u32 s96, s96, 0x4000
	s_addc_u32 s97, s97, 0
	global_load_dword v36, v3, s[96:97] nt
	s_add_u32 s96, s96, 0x4000
	s_addc_u32 s97, s97, 0
	global_load_dword v37, v3, s[96:97] nt
	s_add_u32 s96, s96, 0x4000
	s_addc_u32 s97, s97, 0
	global_load_dword v38, v3, s[96:97] nt
	s_add_u32 s96, s96, 0x4000
	s_addc_u32 s97, s97, 0
	global_load_dword v39, v3, s[96:97] nt
	s_add_u32 s96, s96, 0x4000
	s_addc_u32 s97, s97, 0
	global_load_dword v40, v3, s[96:97] nt
	s_add_u32 s96, s96, 0x4000
	s_addc_u32 s97, s97, 0
	global_load_dword v41, v3, s[96:97] nt
	s_add_u32 s96, s96, 0x4000
	s_addc_u32 s97, s97, 0
	global_load_dword v42, v3, s[96:97] nt
	s_add_u32 s96, s96, 0x4000
	s_addc_u32 s97, s97, 0
	global_load_dword v43, v3, s[96:97] nt
	s_add_u32 s96, s96, 0x4000
	s_addc_u32 s97, s97, 0
	global_load_dword v44, v3, s[96:97] nt
	s_add_u32 s96, s96, 0x4000
	s_addc_u32 s97, s97, 0
	global_load_dword v45, v3, s[96:97] nt
	s_add_u32 s96, s96, 0x4000
	s_addc_u32 s97, s97, 0
	global_load_dword v46, v3, s[96:97] nt
	s_add_u32 s96, s96, 0x4000
	s_addc_u32 s97, s97, 0
	global_load_dword v47, v3, s[96:97] nt
	s_mul_i32 s92, s95, 0x1000
	s_lshl_b32 s93, s91, 7
	s_add_i32 s92, s92, s93
	s_add_u32 s92, s22, s92
	s_addc_u32 s93, s23, 0
	s_add_u32 s92, s92, 0xc80000
	s_addc_u32 s93, s93, 0
	s_waitcnt vmcnt(31)
; #define LAS __attribute__((address_space(3)))
; __device__ __forceinline__ unsigned pk2(float lo, float hi) { const f32x2_t v = {lo, hi}; const bf16x2_t b = __builtin_convertvector(v, bf16x2_t); return __builtin_bit_cast(unsigned, b); }
; #define LDS_WAIT() asm volatile("s_waitcnt lgkmcnt(0)" ::: "memory")
; __device__ __forceinline__ void transpose_item(const float* W, int N, int K, bf16_t* WT, int k0, int n0src, int n0dst, LAS float* scr, int lane) {
;     ...
;     for (int i = 0; i < 32; ++i) scr[(2 * i + (lane >> 5)) * 33 + (lane & 31)] = tv[i];
;     LDS_WAIT();
;     const int c = lane & 7;
; #pragma unroll
;     for (int j = 0; j < 4; ++j) { const int n = (lane >> 3) + 8 * j; const LAS float* s = scr + (8 * c) * 33 + n;
;         u32x4 o; o.x = pk2(s[0 * 33], s[1 * 33]); o.y = pk2(s[2 * 33], s[3 * 33]); o.z = pk2(s[4 * 33], s[5 * 33]); o.w = pk2(s[6 * 33], s[7 * 33]);
;         *(u32x4*)(WT + (size_t)(n0dst + n) * K + k0 + 8 * c) = o; }
;     LDS_WAIT();
; }
; __device__ __forceinline__ void convert_items(const Params& p, LAS float* scr, int lane, int gw, int NGW, int it_lo, int it_hi) {
;     ...
;         if (r < CV_2K) { const int kb = r / 64, nb = r % 64; transpose_item(p.in[16], 2048, 2048, (bf16_t*)(ws + WS_WGU), kb * 64, nb * 32, nb * 32, scr, lane); continue; } r -= CV_2K;
	ds_write_b32 v4, v16
	s_waitcnt vmcnt(30)
	ds_write_b32 v4, v17 offset:264
	s_waitcnt vmcnt(29)
	ds_write_b32 v4, v18 offset:528
	s_waitcnt vmcnt(28)
	ds_write_b32 v4, v19 offset:792
	s_waitcnt vmcnt(27)
	ds_write_b32 v4, v20 offset:1056
	s_waitcnt vmcnt(26)
	ds_write_b32 v4, v21 offset:1320
	s_waitcnt vmcnt(25)
	ds_write_b32 v4, v22 offset:1584
	s_waitcnt vmcnt(24)
	ds_write_b32 v4, v23 offset:1848
	s_waitcnt vmcnt(23)
	ds_write_b32 v4, v24 offset:2112
	s_waitcnt vmcnt(22)
	ds_write_b32 v4, v25 offset:2376
	s_waitcnt vmcnt(21)
	ds_write_b32 v4, v26 offset:2640
	s_waitcnt vmcnt(20)
	ds_write_b32 v4, v27 offset:2904
	s_waitcnt vmcnt(19)
	ds_write_b32 v4, v28 offset:3168
	s_waitcnt vmcnt(18)
	ds_write_b32 v4, v29 offset:3432
	s_waitcnt vmcnt(17)
	ds_write_b32 v4, v30 offset:3696
	s_waitcnt vmcnt(16)
	ds_write_b32 v4, v31 offset:3960
	s_waitcnt vmcnt(15)
	ds_write_b32 v4, v32 offset:4224
	s_waitcnt vmcnt(14)
	ds_write_b32 v4, v33 offset:4488
	s_waitcnt vmcnt(13)
	ds_write_b32 v4, v34 offset:4752
	s_waitcnt vmcnt(12)
	ds_write_b32 v4, v35 offset:5016
	s_waitcnt vmcnt(11)
	ds_write_b32 v4, v36 offset:5280
	s_waitcnt vmcnt(10)
	ds_write_b32 v4, v37 offset:5544
	s_waitcnt vmcnt(9)
	ds_write_b32 v4, v38 offset:5808
	s_waitcnt vmcnt(8)
	ds_write_b32 v4, v39 offset:6072
	s_waitcnt vmcnt(7)
	ds_write_b32 v4, v40 offset:6336
	s_waitcnt vmcnt(6)
	ds_write_b32 v4, v41 offset:6600
	s_waitcnt vmcnt(5)
	ds_write_b32 v4, v42 offset:6864
	s_waitcnt vmcnt(4)
	ds_write_b32 v4, v43 offset:7128
	s_waitcnt vmcnt(3)
	ds_write_b32 v4, v44 offset:7392
	s_waitcnt vmcnt(2)
	ds_write_b32 v4, v45 offset:7656
	s_waitcnt vmcnt(1)
	ds_write_b32 v4, v46 offset:7920
	s_waitcnt vmcnt(0)
	ds_write_b32 v4, v47 offset:8184
	s_waitcnt lgkmcnt(0)
	ds_read_b32 v48, v7
	ds_read_b32 v49, v7 offset:132
	ds_read_b32 v50, v7 offset:264
	ds_read_b32 v51, v7 offset:396
	ds_read_b32 v52, v7 offset:528
	ds_read_b32 v53, v7 offset:660
	ds_read_b32 v54, v7 offset:792
	ds_read_b32 v55, v7 offset:924
	s_waitcnt lgkmcnt(0)
	v_cvt_pk_bf16_f32 v80, v48, v49
	v_cvt_pk_bf16_f32 v81, v50, v51
	v_cvt_pk_bf16_f32 v82, v52, v53
	v_cvt_pk_bf16_f32 v83, v54, v55
	global_store_dwordx4 v8, v[80:83], s[92:93]
	ds_read_b32 v56, v7 offset:32
	ds_read_b32 v57, v7 offset:164
	ds_read_b32 v58, v7 offset:296
	ds_read_b32 v59, v7 offset:428
	ds_read_b32 v60, v7 offset:560
	ds_read_b32 v61, v7 offset:692
	ds_read_b32 v62, v7 offset:824
	ds_read_b32 v63, v7 offset:956
	s_waitcnt lgkmcnt(0)
	v_cvt_pk_bf16_f32 v84, v56, v57
	v_cvt_pk_bf16_f32 v85, v58, v59
	v_cvt_pk_bf16_f32 v86, v60, v61
	v_cvt_pk_bf16_f32 v87, v62, v63
	global_store_dwordx4 v9, v[84:87], s[92:93]
	ds_read_b32 v64, v7 offset:64
	ds_read_b32 v65, v7 offset:196
	ds_read_b32 v66, v7 offset:328
	ds_read_b32 v67, v7 offset:460
	ds_read_b32 v68, v7 offset:592
	ds_read_b32 v69, v7 offset:724
	ds_read_b32 v70, v7 offset:856
	ds_read_b32 v71, v7 offset:988
	s_waitcnt lgkmcnt(0)
	v_cvt_pk_bf16_f32 v88, v64, v65
	v_cvt_pk_bf16_f32 v89, v66, v67
	v_cvt_pk_bf16_f32 v90, v68, v69
	v_cvt_pk_bf16_f32 v91, v70, v71
	global_store_dwordx4 v10, v[88:91], s[92:93]
	ds_read_b32 v72, v7 offset:96
	ds_read_b32 v73, v7 offset:228
	ds_read_b32 v74, v7 offset:360
	ds_read_b32 v75, v7 offset:492
	ds_read_b32 v76, v7 offset:624
	ds_read_b32 v77, v7 offset:756
	ds_read_b32 v78, v7 offset:888
	ds_read_b32 v79, v7 offset:1020
	s_waitcnt lgkmcnt(0)
	v_cvt_pk_bf16_f32 v92, v72, v73
	v_cvt_pk_bf16_f32 v93, v74, v75
	v_cvt_pk_bf16_f32 v94, v76, v77
	v_cvt_pk_bf16_f32 v95, v78, v79
	global_store_dwordx4 v11, v[92:95], s[92:93]
	s_add_i32 s85, s85, 0x600
	s_branch .Lgconv_wo_loop
.Lgconv_wo_done:
	s_mov_b64 exec, -1
	v_mbcnt_lo_u32_b32 v0, -1, 0
	v_mbcnt_hi_u32_b32 v0, -1, v0
	s_lshr_b32 s84, s24, 6
	s_sub_i32 s85, s2, 64
	s_lshl_b32 s85, s85, 3
	s_add_i32 s85, s85, s84
	v_readlane_b32 s86, v254, 0
	v_readlane_b32 s87, v254, 1
	s_mul_i32 s90, s84, 0x2100
	v_lshrrev_b32_e32 v1, 5, v0
	v_and_b32_e32 v2, 31, v0
	v_mul_u32_u24_e32 v3, 0x2000, v1
	v_lshl_add_u32 v3, v2, 2, v3
	v_mul_u32_u24_e32 v4, 33, v1
	v_add_u32_e32 v4, v4, v2
	v_lshl_add_u32 v4, v4, 2, s90
	v_and_b32_e32 v5, 7, v0
	v_lshrrev_b32_e32 v6, 3, v0
	v_mul_u32_u24_e32 v7, 0x420, v5
	v_lshl_add_u32 v7, v6, 2, v7
	v_add_u32_e32 v7, s90, v7
	v_mul_u32_u24_e32 v8, 0x1000, v6
	v_lshl_add_u32 v8, v5, 4, v8
	v_add_u32_e32 v9, 0x8000, v8
	v_add_u32_e32 v10, 0x10000, v8
	v_add_u32_e32 v11, 0x18000, v8
; #define LAS __attribute__((address_space(3)))
; __device__ __forceinline__ unsigned pk2(float lo, float hi) { const f32x2_t v = {lo, hi}; const bf16x2_t b = __builtin_convertvector(v, bf16x2_t); return __builtin_bit_cast(unsigned, b); }
; #define LDS_WAIT() asm volatile("s_waitcnt lgkmcnt(0)" ::: "memory")
; __device__ __forceinline__ void transpose_item(const float* W, int N, int K, bf16_t* WT, int k0, int n0src, int n0dst, LAS float* scr, int lane) {
;     float tv[32];
; #pragma unroll
;     for (int i = 0; i < 32; ++i) tv[i] = __builtin_nontemporal_load(&W[(size_t)(k0 + 2 * i + (lane >> 5)) * N + n0src + (lane & 31)]);
; #pragma unroll
;     for (int i = 0; i < 32; ++i) scr[(2 * i + (lane >> 5)) * 33 + (lane & 31)] = tv[i];
;     LDS_WAIT();
;     const int c = lane & 7;
; #pragma unroll
;     for (int j = 0; j < 4; ++j) { const int n = (lane >> 3) + 8 * j; const LAS float* s = scr + (8 * c) * 33 + n;
;         u32x4 o; o.x = pk2(s[0 * 33], s[1 * 33]); o.y = pk2(s[2 * 33], s[3 * 33]); o.z = pk2(s[4 * 33], s[5 * 33]); o.w = pk2(s[6 * 33], s[7 * 33]);
;         *(u32x4*)(WT + (size_t)(n0dst + n) * K + k0 + 8 * c) = o; }
;     LDS_WAIT();
; }
; __device__ __forceinline__ void convert_items(const Params& p, LAS float* scr, int lane, int gw, int NGW, int it_lo, int it_hi) {
;     ...
;         if (r < CV_2K) { const int kb = r / 64, nb = r % 64; transpose_item(p.in[16], 2048, 2048, (bf16_t*)(ws + WS_WGU), kb * 64, nb * 32, nb * 32, scr, lane); continue; } r -= CV_2K;
.Lgconv_wgu_loop:
	s_cmp_lt_u32 s85, 0x800
	s_cbranch_scc0 .Lgconv_wgu_done
	s_lshr_b32 s91, s85, 6
	s_mul_i32 s92, s91, 0x40
	s_sub_i32 s92, s85, s92
	s_lshl_b32 s92, s92, 5
	s_mov_b32 s95, s92
	s_mul_i32 s96, s91, 0x80000
	s_lshl_b32 s97, s92, 2
	s_add_i32 s96, s96, s97
	s_add_u32 s96, s86, s96
	s_addc_u32 s97, s87, 0
	global_load_dword v16, v3, s[96:97] nt
	s_add_u32 s96, s96, 0x4000
	s_addc_u32 s97, s97, 0
	global_load_dword v17, v3, s[96:97] nt
	s_add_u32 s96, s96, 0x4000
	s_addc_u32 s97, s97, 0
	global_load_dword v18, v3, s[96:97] nt
	s_add_u32 s96, s96, 0x4000
	s_addc_u32 s97, s97, 0
	global_load_dword v19, v3, s[96:97] nt
	s_add_u32 s96, s96, 0x4000
	s_addc_u32 s97, s97, 0
	global_load_dword v20, v3, s[96:97] nt
	s_add_u32 s96, s96, 0x4000
	s_addc_u32 s97, s97, 0
	global_load_dword v21, v3, s[96:97] nt
	s_add_u32 s96, s96, 0x4000
	s_addc_u32 s97, s97, 0
	global_load_dword v22, v3, s[96:97] nt
	s_add_u32 s96, s96, 0x4000
	s_addc_u32 s97, s97, 0
	global_load_dword v23, v3, s[96:97] nt
	s_add_u32 s96, s96, 0x4000
	s_addc_u32 s97, s97, 0
	global_load_dword v24, v3, s[96:97] nt
	s_add_u32 s96, s96, 0x4000
	s_addc_u32 s97, s97, 0
	global_load_dword v25, v3, s[96:97] nt
	s_add_u32 s96, s96, 0x4000
	s_addc_u32 s97, s97, 0
	global_load_dword v26, v3, s[96:97] nt
	s_add_u32 s96, s96, 0x4000
	s_addc_u32 s97, s97, 0
	global_load_dword v27, v3, s[96:97] nt
	s_add_u32 s96, s96, 0x4000
	s_addc_u32 s97, s97, 0
	global_load_dword v28, v3, s[96:97] nt
	s_add_u32 s96, s96, 0x4000
	s_addc_u32 s97, s97, 0
	global_load_dword v29, v3, s[96:97] nt
	s_add_u32 s96, s96, 0x4000
	s_addc_u32 s97, s97, 0
	global_load_dword v30, v3, s[96:97] nt
	s_add_u32 s96, s96, 0x4000
	s_addc_u32 s97, s97, 0
	global_load_dword v31, v3, s[96:97] nt
	s_add_u32 s96, s96, 0x4000
	s_addc_u32 s97, s97, 0
	global_load_dword v32, v3, s[96:97] nt
	s_add_u32 s96, s96, 0x4000
	s_addc_u32 s97, s97, 0
	global_load_dword v33, v3, s[96:97] nt
	s_add_u32 s96, s96, 0x4000
	s_addc_u32 s97, s97, 0
	global_load_dword v34, v3, s[96:97] nt
	s_add_u32 s96, s96, 0x4000
	s_addc_u32 s97, s97, 0
	global_load_dword v35, v3, s[96:97] nt
	s_add_u32 s96, s96, 0x4000
	s_addc_u32 s97, s97, 0
	global_load_dword v36, v3, s[96:97] nt
	s_add_u32 s96, s96, 0x4000
	s_addc_u32 s97, s97, 0
	global_load_dword v37, v3, s[96:97] nt
	s_add_u32 s96, s96, 0x4000
	s_addc_u32 s97, s97, 0
	global_load_dword v38, v3, s[96:97] nt
	s_add_u32 s96, s96, 0x4000
	s_addc_u32 s97, s97, 0
	global_load_dword v39, v3, s[96:97] nt
	s_add_u32 s96, s96, 0x4000
	s_addc_u32 s97, s97, 0
	global_load_dword v40, v3, s[96:97] nt
	s_add_u32 s96, s96, 0x4000
	s_addc_u32 s97, s97, 0
	global_load_dword v41, v3, s[96:97] nt
	s_add_u32 s96, s96, 0x4000
	s_addc_u32 s97, s97, 0
	global_load_dword v42, v3, s[96:97] nt
	s_add_u32 s96, s96, 0x4000
	s_addc_u32 s97, s97, 0
	global_load_dword v43, v3, s[96:97] nt
	s_add_u32 s96, s96, 0x4000
	s_addc_u32 s97, s97, 0
	global_load_dword v44, v3, s[96:97] nt
	s_add_u32 s96, s96, 0x4000
	s_addc_u32 s97, s97, 0
	global_load_dword v45, v3, s[96:97] nt
	s_add_u32 s96, s96, 0x4000
	s_addc_u32 s97, s97, 0
	global_load_dword v46, v3, s[96:97] nt
	s_add_u32 s96, s96, 0x4000
	s_addc_u32 s97, s97, 0
	global_load_dword v47, v3, s[96:97] nt
	s_mul_i32 s92, s95, 0x1000
	s_lshl_b32 s93, s91, 7
	s_add_i32 s92, s92, s93
	s_add_u32 s92, s22, s92
	s_addc_u32 s93, s23, 0
	s_add_u32 s92, s92, 0x480000
	s_addc_u32 s93, s93, 0
	s_waitcnt vmcnt(31)
	ds_write_b32 v4, v16
	s_waitcnt vmcnt(30)
	ds_write_b32 v4, v17 offset:264
	s_waitcnt vmcnt(29)
	ds_write_b32 v4, v18 offset:528
	s_waitcnt vmcnt(28)
	ds_write_b32 v4, v19 offset:792
	s_waitcnt vmcnt(27)
	ds_write_b32 v4, v20 offset:1056
	s_waitcnt vmcnt(26)
	ds_write_b32 v4, v21 offset:1320
	s_waitcnt vmcnt(25)
	ds_write_b32 v4, v22 offset:1584
	s_waitcnt vmcnt(24)
	ds_write_b32 v4, v23 offset:1848
	s_waitcnt vmcnt(23)
	ds_write_b32 v4, v24 offset:2112
	s_waitcnt vmcnt(22)
	ds_write_b32 v4, v25 offset:2376
	s_waitcnt vmcnt(21)
	ds_write_b32 v4, v26 offset:2640
	s_waitcnt vmcnt(20)
	ds_write_b32 v4, v27 offset:2904
	s_waitcnt vmcnt(19)
	ds_write_b32 v4, v28 offset:3168
	s_waitcnt vmcnt(18)
	ds_write_b32 v4, v29 offset:3432
	s_waitcnt vmcnt(17)
	ds_write_b32 v4, v30 offset:3696
	s_waitcnt vmcnt(16)
	ds_write_b32 v4, v31 offset:3960
	s_waitcnt vmcnt(15)
	ds_write_b32 v4, v32 offset:4224
	s_waitcnt vmcnt(14)
	ds_write_b32 v4, v33 offset:4488
	s_waitcnt vmcnt(13)
	ds_write_b32 v4, v34 offset:4752
	s_waitcnt vmcnt(12)
	ds_write_b32 v4, v35 offset:5016
	s_waitcnt vmcnt(11)
	ds_write_b32 v4, v36 offset:5280
	s_waitcnt vmcnt(10)
	ds_write_b32 v4, v37 offset:5544
	s_waitcnt vmcnt(9)
	ds_write_b32 v4, v38 offset:5808
	s_waitcnt vmcnt(8)
	ds_write_b32 v4, v39 offset:6072
	s_waitcnt vmcnt(7)
	ds_write_b32 v4, v40 offset:6336
	s_waitcnt vmcnt(6)
	ds_write_b32 v4, v41 offset:6600
	s_waitcnt vmcnt(5)
	ds_write_b32 v4, v42 offset:6864
	s_waitcnt vmcnt(4)
	ds_write_b32 v4, v43 offset:7128
	s_waitcnt vmcnt(3)
	ds_write_b32 v4, v44 offset:7392
	s_waitcnt vmcnt(2)
	ds_write_b32 v4, v45 offset:7656
	s_waitcnt vmcnt(1)
	ds_write_b32 v4, v46 offset:7920
	s_waitcnt vmcnt(0)
	ds_write_b32 v4, v47 offset:8184
	s_waitcnt lgkmcnt(0)
	ds_read_b32 v48, v7
	ds_read_b32 v49, v7 offset:132
	ds_read_b32 v50, v7 offset:264
	ds_read_b32 v51, v7 offset:396
	ds_read_b32 v52, v7 offset:528
	ds_read_b32 v53, v7 offset:660
	ds_read_b32 v54, v7 offset:792
	ds_read_b32 v55, v7 offset:924
	s_waitcnt lgkmcnt(0)
	v_cvt_pk_bf16_f32 v80, v48, v49
	v_cvt_pk_bf16_f32 v81, v50, v51
	v_cvt_pk_bf16_f32 v82, v52, v53
	v_cvt_pk_bf16_f32 v83, v54, v55
	global_store_dwordx4 v8, v[80:83], s[92:93]
	ds_read_b32 v56, v7 offset:32
	ds_read_b32 v57, v7 offset:164
	ds_read_b32 v58, v7 offset:296
	ds_read_b32 v59, v7 offset:428
	ds_read_b32 v60, v7 offset:560
	ds_read_b32 v61, v7 offset:692
	ds_read_b32 v62, v7 offset:824
	ds_read_b32 v63, v7 offset:956
	s_waitcnt lgkmcnt(0)
	v_cvt_pk_bf16_f32 v84, v56, v57
	v_cvt_pk_bf16_f32 v85, v58, v59
	v_cvt_pk_bf16_f32 v86, v60, v61
	v_cvt_pk_bf16_f32 v87, v62, v63
	global_store_dwordx4 v9, v[84:87], s[92:93]
	ds_read_b32 v64, v7 offset:64
	ds_read_b32 v65, v7 offset:196
	ds_read_b32 v66, v7 offset:328
	ds_read_b32 v67, v7 offset:460
	ds_read_b32 v68, v7 offset:592
	ds_read_b32 v69, v7 offset:724
	ds_read_b32 v70, v7 offset:856
	ds_read_b32 v71, v7 offset:988
	s_waitcnt lgkmcnt(0)
	v_cvt_pk_bf16_f32 v88, v64, v65
	v_cvt_pk_bf16_f32 v89, v66, v67
	v_cvt_pk_bf16_f32 v90, v68, v69
	v_cvt_pk_bf16_f32 v91, v70, v71
	global_store_dwordx4 v10, v[88:91], s[92:93]
	ds_read_b32 v72, v7 offset:96
	ds_read_b32 v73, v7 offset:228
	ds_read_b32 v74, v7 offset:360
	ds_read_b32 v75, v7 offset:492
	ds_read_b32 v76, v7 offset:624
	ds_read_b32 v77, v7 offset:756
	ds_read_b32 v78, v7 offset:888
	ds_read_b32 v79, v7 offset:1020
	s_waitcnt lgkmcnt(0)
	v_cvt_pk_bf16_f32 v92, v72, v73
	v_cvt_pk_bf16_f32 v93, v74, v75
	v_cvt_pk_bf16_f32 v94, v76, v77
	v_cvt_pk_bf16_f32 v95, v78, v79
	global_store_dwordx4 v11, v[92:95], s[92:93]
	s_add_i32 s85, s85, 0x600
	s_branch .Lgconv_wgu_loop
